# grid barrier: non-leader workgroups poll the cross-XCD release generation directly (one relay hop less)
# speedup vs baseline: 1.0062x; 1.0062x over previous
; __device__ __forceinline__ unsigned xb_ld(unsigned* p)              { return __hip_atomic_load(p, __ATOMIC_RELAXED, __HIP_MEMORY_SCOPE_AGENT); }
; __device__ __forceinline__ unsigned xb_add(unsigned* p, unsigned v) { return __hip_atomic_fetch_add(p, v, __ATOMIC_RELAXED, __HIP_MEMORY_SCOPE_AGENT); }
; #define XB_SPIN(cond, bar) do { unsigned _sp = 0; while (cond) { __builtin_amdgcn_s_sleep(1); \
;     if ((++_sp & 255u) == 0u) { if (xb_ld(&(bar)[XB_TMO])) break; if (_sp > XB_SPIN_CAP) { atomicAdd(&(bar)[XB_TMO], 1u); break; } } } } while (0)
; __device__ __forceinline__ void xcd_barrier(const XcdBarrier& b) {
;     ...
;         unsigned nloc = b.st[0], nx = b.st[1];
;         if (nloc == 0u) { xcd_barrier_complete(bar, b.x, nloc, nx); b.st[0] = nloc; b.st[1] = nx; }
;         const unsigned old = xb_add(&bar[XB_XSUB(b.x)], 1u);
;         const unsigned gen = old / nloc;
;         if (old + 1u == (gen + 1u) * nloc) {
;             __builtin_amdgcn_fence(__ATOMIC_RELEASE, "agent");
;             asm volatile("s_waitcnt vmcnt(0)" ::: "memory");
;             const unsigned og = xb_add(&bar[XB_TOP], 1u);
;             const unsigned tg = og / nx;
;             if (og + 1u == (tg + 1u) * nx) xb_add(&bar[XB_TOPGEN], 1u);
;             else XB_SPIN(xb_ld(&bar[XB_TOPGEN]) == tg, bar);
;     ...
;             XB_SPIN(xb_ld(&bar[XB_XGEN(b.x)]) == gen, bar);
.LBB0_165:
	s_or_b64 exec, exec, s[8:9]
	v_cvt_f32_u32_e32 v5, v3
	s_waitcnt vmcnt(0)
	v_readfirstlane_b32 s6, v4
	v_sub_u32_e32 v4, 0, v3
	v_rcp_iflag_f32_e32 v5, v5
	v_add_u32_e32 v6, s6, v2
	v_mul_f32_e32 v5, 0x4f7ffffe, v5
	v_cvt_u32_f32_e32 v5, v5
	v_mul_lo_u32 v2, v4, v5
	v_mul_hi_u32 v2, v5, v2
	v_add_u32_e32 v2, v5, v2
	v_mul_hi_u32 v2, v6, v2
	v_mul_lo_u32 v4, v2, v3
	v_sub_u32_e32 v4, v6, v4
	v_add_u32_e32 v5, 1, v2
	v_cmp_ge_u32_e32 vcc, v4, v3
	s_nop 1
	v_cndmask_b32_e32 v2, v2, v5, vcc
	v_sub_u32_e32 v5, v4, v3
	v_cndmask_b32_e32 v4, v4, v5, vcc
	v_add_u32_e32 v5, 1, v2
	v_cmp_ge_u32_e32 vcc, v4, v3
	v_add_u32_e32 v4, 1, v6
	s_nop 0
	v_cndmask_b32_e32 v2, v2, v5, vcc
	v_mul_lo_u32 v5, v3, v2
	v_add_u32_e32 v3, v5, v3
	v_cmp_ne_u32_e32 vcc, v4, v3
	s_and_saveexec_b64 s[6:7], vcc
	s_xor_b64 s[6:7], exec, s[6:7]
	s_cbranch_execz .LBB0_179
	s_waitcnt lgkmcnt(0)
	v_mov_b32_e32 v1, 0x2000
	s_add_u32 s12, s90, 0x7500
	s_addc_u32 s13, s91, 0
	v_mov_b32_e32 v1, 0
	global_load_dword v1, v1, s[12:13] sc1
	s_waitcnt vmcnt(0)
	v_cmp_eq_u32_e32 vcc, v1, v2
	s_and_saveexec_b64 s[8:9], vcc
	s_cbranch_execz .LBB0_178
	s_add_u32 s10, s90, 0x4200
	s_addc_u32 s11, s91, 0
	s_mov_b32 s24, 1
	s_mov_b64 s[14:15], 0
	v_mov_b32_e32 v1, 0
	s_branch .LBB0_169

; __device__ __forceinline__ unsigned xb_ld(unsigned* p)              { return __hip_atomic_load(p, __ATOMIC_RELAXED, __HIP_MEMORY_SCOPE_AGENT); }
; __device__ __forceinline__ unsigned xb_add(unsigned* p, unsigned v) { return __hip_atomic_fetch_add(p, v, __ATOMIC_RELAXED, __HIP_MEMORY_SCOPE_AGENT); }
; #define XB_SPIN(cond, bar) do { unsigned _sp = 0; while (cond) { __builtin_amdgcn_s_sleep(1); \
;     if ((++_sp & 255u) == 0u) { if (xb_ld(&(bar)[XB_TMO])) break; if (_sp > XB_SPIN_CAP) { atomicAdd(&(bar)[XB_TMO], 1u); break; } } } } while (0)
; __device__ __forceinline__ void xcd_barrier(const XcdBarrier& b) {
;     ...
;         unsigned nloc = b.st[0], nx = b.st[1];
;         if (nloc == 0u) { xcd_barrier_complete(bar, b.x, nloc, nx); b.st[0] = nloc; b.st[1] = nx; }
;         const unsigned old = xb_add(&bar[XB_XSUB(b.x)], 1u);
;         const unsigned gen = old / nloc;
;         if (old + 1u == (gen + 1u) * nloc) {
;             __builtin_amdgcn_fence(__ATOMIC_RELEASE, "agent");
;             asm volatile("s_waitcnt vmcnt(0)" ::: "memory");
;             const unsigned og = xb_add(&bar[XB_TOP], 1u);
;             const unsigned tg = og / nx;
;             if (og + 1u == (tg + 1u) * nx) xb_add(&bar[XB_TOPGEN], 1u);
;             else XB_SPIN(xb_ld(&bar[XB_TOPGEN]) == tg, bar);
;             __builtin_amdgcn_fence(__ATOMIC_ACQUIRE, "agent");
;             xb_add(&bar[XB_XGEN(b.x)], 1u);
;             asm volatile("s_waitcnt vmcnt(0)" ::: "memory");
;         } else {
;             XB_SPIN(xb_ld(&bar[XB_XGEN(b.x)]) == gen, bar);
.LBB0_709:
	s_or_b64 exec, exec, s[4:5]
	v_cvt_f32_u32_e32 v6, v4
	s_waitcnt vmcnt(0)
	v_readfirstlane_b32 s4, v5
	v_sub_u32_e32 v5, 0, v4
	v_rcp_iflag_f32_e32 v6, v6
	v_add_u32_e32 v7, s4, v3
	v_mul_f32_e32 v6, 0x4f7ffffe, v6
	v_cvt_u32_f32_e32 v6, v6
	v_mul_lo_u32 v3, v5, v6
	v_mul_hi_u32 v3, v6, v3
	v_add_u32_e32 v3, v6, v3
	v_mul_hi_u32 v3, v7, v3
	v_mul_lo_u32 v5, v3, v4
	v_sub_u32_e32 v5, v7, v5
	v_add_u32_e32 v6, 1, v3
	v_cmp_ge_u32_e32 vcc, v5, v4
	s_nop 1
	v_cndmask_b32_e32 v3, v3, v6, vcc
	v_sub_u32_e32 v6, v5, v4
	v_cndmask_b32_e32 v5, v5, v6, vcc
	v_add_u32_e32 v6, 1, v3
	v_cmp_ge_u32_e32 vcc, v5, v4
	v_add_u32_e32 v5, 1, v7
	s_nop 0
	v_cndmask_b32_e32 v3, v3, v6, vcc
	v_mul_lo_u32 v6, v4, v3
	v_add_u32_e32 v4, v6, v4
	v_cmp_ne_u32_e32 vcc, v5, v4
	s_and_saveexec_b64 s[4:5], vcc
	s_xor_b64 s[4:5], exec, s[4:5]
	s_cbranch_execz .LBB0_723
	v_readlane_b32 s6, v252, 31
	v_readlane_b32 s7, v252, 32
	s_waitcnt lgkmcnt(0)
	s_nop 3
	global_load_dword v2, v195, s[6:7] sc1
	s_waitcnt vmcnt(0)
	v_cmp_eq_u32_e32 vcc, v2, v3
	s_and_saveexec_b64 s[6:7], vcc
	s_cbranch_execz .LBB0_722
	s_mov_b32 s19, 1
	s_mov_b64 s[8:9], 0
	s_branch .LBB0_713

; __device__ __forceinline__ unsigned xb_ld(unsigned* p)              { return __hip_atomic_load(p, __ATOMIC_RELAXED, __HIP_MEMORY_SCOPE_AGENT); }
; #define XB_SPIN(cond, bar) do { unsigned _sp = 0; while (cond) { __builtin_amdgcn_s_sleep(1); \
;     if ((++_sp & 255u) == 0u) { if (xb_ld(&(bar)[XB_TMO])) break; if (_sp > XB_SPIN_CAP) { atomicAdd(&(bar)[XB_TMO], 1u); break; } } } } while (0)
; __device__ __forceinline__ void xcd_barrier(const XcdBarrier& b) {
;     ...
;             XB_SPIN(xb_ld(&bar[XB_XGEN(b.x)]) == gen, bar);
.LBB0_715:
	v_readlane_b32 s12, v252, 31
	v_readlane_b32 s13, v252, 32
	s_add_i32 s19, s19, 1
	s_mov_b64 s[14:15], -1
	s_nop 2
	global_load_dword v2, v195, s[12:13] sc1
	s_waitcnt vmcnt(0)
	v_cmp_ne_u32_e32 vcc, v2, v3
	s_orn2_b64 s[12:13], vcc, exec
	s_branch .LBB0_712
